# byte-placement trial: one nop ahead of the merge T K-loop puts it and the outproj K-loop on 8-byte-aligned heads (M loop unchanged)
# speedup vs baseline: 1.0044x; 1.0010x over previous
; DI unsigned pack2(float a, float b) { f32v2 v = {a, b}; return __builtin_bit_cast(unsigned, __builtin_convertvector(v, bf16v2)); }
; DI float sigm_fast(float x) { return __builtin_amdgcn_rcpf(1.f + __expf(-x)); }
; DI void phase_merge(const Params& p, int l, char* smem, int tid) {
;     ...
; #pragma unroll
;         for (int b2 = 0; b2 < 2; b2++)
; #pragma unroll
;           for (int e = 0; e < 8; e++) sg[b2][e] = pack2(sigm_fast(m[0][b2][2 * e]), sigm_fast(m[0][b2][2 * e + 1]));
.Lmgm_kdone:
	s_nop 7
	s_nop 7
	v_mul_f32_e32 v66, 0xbfb8aa3b, v66
	v_mul_f32_e32 v67, 0xbfb8aa3b, v67
	v_mul_f32_e32 v68, 0xbfb8aa3b, v68
	v_mul_f32_e32 v69, 0xbfb8aa3b, v69
	v_mul_f32_e32 v70, 0xbfb8aa3b, v70
	v_mul_f32_e32 v71, 0xbfb8aa3b, v71
	v_mul_f32_e32 v72, 0xbfb8aa3b, v72
	v_mul_f32_e32 v73, 0xbfb8aa3b, v73
	v_exp_f32_e32 v66, v66
	v_exp_f32_e32 v67, v67
	v_exp_f32_e32 v68, v68
	v_exp_f32_e32 v69, v69
	v_exp_f32_e32 v70, v70
	v_exp_f32_e32 v71, v71
	v_exp_f32_e32 v72, v72
	v_exp_f32_e32 v73, v73
	v_add_f32_e32 v66, 1.0, v66
	v_add_f32_e32 v67, 1.0, v67
	v_add_f32_e32 v68, 1.0, v68
	v_add_f32_e32 v69, 1.0, v69
	v_add_f32_e32 v70, 1.0, v70
	v_add_f32_e32 v71, 1.0, v71
	v_add_f32_e32 v72, 1.0, v72
	v_add_f32_e32 v73, 1.0, v73
	v_rcp_f32_e32 v66, v66
	v_rcp_f32_e32 v67, v67
	v_rcp_f32_e32 v68, v68
	v_rcp_f32_e32 v69, v69
	v_rcp_f32_e32 v70, v70
	v_rcp_f32_e32 v71, v71
	v_rcp_f32_e32 v72, v72
	v_rcp_f32_e32 v73, v73
	s_nop 0
	v_cvt_pk_bf16_f32 v156, v66, v67
	v_cvt_pk_bf16_f32 v157, v68, v69
	v_cvt_pk_bf16_f32 v158, v70, v71
	v_cvt_pk_bf16_f32 v159, v72, v73
	v_mul_f32_e32 v74, 0xbfb8aa3b, v74
	v_mul_f32_e32 v75, 0xbfb8aa3b, v75
	v_mul_f32_e32 v76, 0xbfb8aa3b, v76
	v_mul_f32_e32 v77, 0xbfb8aa3b, v77
	v_mul_f32_e32 v78, 0xbfb8aa3b, v78
	v_mul_f32_e32 v79, 0xbfb8aa3b, v79
	v_mul_f32_e32 v80, 0xbfb8aa3b, v80
	v_mul_f32_e32 v81, 0xbfb8aa3b, v81
	v_exp_f32_e32 v74, v74
	v_exp_f32_e32 v75, v75
	v_exp_f32_e32 v76, v76
	v_exp_f32_e32 v77, v77
	v_exp_f32_e32 v78, v78
	v_exp_f32_e32 v79, v79
	v_exp_f32_e32 v80, v80
	v_exp_f32_e32 v81, v81
	v_add_f32_e32 v74, 1.0, v74
	v_add_f32_e32 v75, 1.0, v75
	v_add_f32_e32 v76, 1.0, v76
	v_add_f32_e32 v77, 1.0, v77
	v_add_f32_e32 v78, 1.0, v78
	v_add_f32_e32 v79, 1.0, v79
	v_add_f32_e32 v80, 1.0, v80
	v_add_f32_e32 v81, 1.0, v81
	v_rcp_f32_e32 v74, v74
	v_rcp_f32_e32 v75, v75
	v_rcp_f32_e32 v76, v76
	v_rcp_f32_e32 v77, v77
	v_rcp_f32_e32 v78, v78
	v_rcp_f32_e32 v79, v79
	v_rcp_f32_e32 v80, v80
	v_rcp_f32_e32 v81, v81
	s_nop 0
	v_cvt_pk_bf16_f32 v160, v74, v75
	v_cvt_pk_bf16_f32 v161, v76, v77
	v_cvt_pk_bf16_f32 v162, v78, v79
	v_cvt_pk_bf16_f32 v163, v80, v81
	v_mul_f32_e32 v82, 0xbfb8aa3b, v82
	v_mul_f32_e32 v83, 0xbfb8aa3b, v83
	v_mul_f32_e32 v84, 0xbfb8aa3b, v84
	v_mul_f32_e32 v85, 0xbfb8aa3b, v85
	v_mul_f32_e32 v86, 0xbfb8aa3b, v86
	v_mul_f32_e32 v87, 0xbfb8aa3b, v87
	v_mul_f32_e32 v88, 0xbfb8aa3b, v88
	v_mul_f32_e32 v89, 0xbfb8aa3b, v89
	v_exp_f32_e32 v82, v82
	v_exp_f32_e32 v83, v83
	v_exp_f32_e32 v84, v84
	v_exp_f32_e32 v85, v85
	v_exp_f32_e32 v86, v86
	v_exp_f32_e32 v87, v87
	v_exp_f32_e32 v88, v88
	v_exp_f32_e32 v89, v89
	v_add_f32_e32 v82, 1.0, v82
	v_add_f32_e32 v83, 1.0, v83
	v_add_f32_e32 v84, 1.0, v84
	v_add_f32_e32 v85, 1.0, v85
	v_add_f32_e32 v86, 1.0, v86
	v_add_f32_e32 v87, 1.0, v87
	v_add_f32_e32 v88, 1.0, v88
	v_add_f32_e32 v89, 1.0, v89
	v_rcp_f32_e32 v82, v82
	v_rcp_f32_e32 v83, v83
	v_rcp_f32_e32 v84, v84
	v_rcp_f32_e32 v85, v85
	v_rcp_f32_e32 v86, v86
	v_rcp_f32_e32 v87, v87
	v_rcp_f32_e32 v88, v88
	v_rcp_f32_e32 v89, v89
	s_nop 0
	v_cvt_pk_bf16_f32 v164, v82, v83
	v_cvt_pk_bf16_f32 v165, v84, v85
	v_cvt_pk_bf16_f32 v166, v86, v87
	v_cvt_pk_bf16_f32 v167, v88, v89
	v_mul_f32_e32 v90, 0xbfb8aa3b, v90
	v_mul_f32_e32 v91, 0xbfb8aa3b, v91
	v_mul_f32_e32 v92, 0xbfb8aa3b, v92
	v_mul_f32_e32 v93, 0xbfb8aa3b, v93
	v_mul_f32_e32 v94, 0xbfb8aa3b, v94
	v_mul_f32_e32 v95, 0xbfb8aa3b, v95
	v_mul_f32_e32 v96, 0xbfb8aa3b, v96
	v_mul_f32_e32 v97, 0xbfb8aa3b, v97
	v_exp_f32_e32 v90, v90
	v_exp_f32_e32 v91, v91
	v_exp_f32_e32 v92, v92
	v_exp_f32_e32 v93, v93
	v_exp_f32_e32 v94, v94
	v_exp_f32_e32 v95, v95
	v_exp_f32_e32 v96, v96
	v_exp_f32_e32 v97, v97
	v_add_f32_e32 v90, 1.0, v90
	v_add_f32_e32 v91, 1.0, v91
	v_add_f32_e32 v92, 1.0, v92
	v_add_f32_e32 v93, 1.0, v93
	v_add_f32_e32 v94, 1.0, v94
	v_add_f32_e32 v95, 1.0, v95
	v_add_f32_e32 v96, 1.0, v96
	v_add_f32_e32 v97, 1.0, v97
	v_rcp_f32_e32 v90, v90
	v_rcp_f32_e32 v91, v91
	v_rcp_f32_e32 v92, v92
	v_rcp_f32_e32 v93, v93
	v_rcp_f32_e32 v94, v94
	v_rcp_f32_e32 v95, v95
	v_rcp_f32_e32 v96, v96
	v_rcp_f32_e32 v97, v97
	s_nop 0
	v_cvt_pk_bf16_f32 v168, v90, v91
	v_cvt_pk_bf16_f32 v169, v92, v93
	v_cvt_pk_bf16_f32 v170, v94, v95
	v_cvt_pk_bf16_f32 v171, v96, v97
	v_mul_f32_e32 v98, 0xbfb8aa3b, v98
	v_mul_f32_e32 v99, 0xbfb8aa3b, v99
	v_mul_f32_e32 v100, 0xbfb8aa3b, v100
	v_mul_f32_e32 v101, 0xbfb8aa3b, v101
	v_mul_f32_e32 v102, 0xbfb8aa3b, v102
	v_mul_f32_e32 v103, 0xbfb8aa3b, v103
	v_mul_f32_e32 v104, 0xbfb8aa3b, v104
	v_mul_f32_e32 v105, 0xbfb8aa3b, v105
	v_exp_f32_e32 v98, v98
	v_exp_f32_e32 v99, v99
	v_exp_f32_e32 v100, v100
	v_exp_f32_e32 v101, v101
	v_exp_f32_e32 v102, v102
	v_exp_f32_e32 v103, v103
	v_exp_f32_e32 v104, v104
	v_exp_f32_e32 v105, v105
	v_add_f32_e32 v98, 1.0, v98
	v_add_f32_e32 v99, 1.0, v99
	v_add_f32_e32 v100, 1.0, v100
	v_add_f32_e32 v101, 1.0, v101
	v_add_f32_e32 v102, 1.0, v102
	v_add_f32_e32 v103, 1.0, v103
	v_add_f32_e32 v104, 1.0, v104
	v_add_f32_e32 v105, 1.0, v105
	v_rcp_f32_e32 v98, v98
	v_rcp_f32_e32 v99, v99
	v_rcp_f32_e32 v100, v100
	v_rcp_f32_e32 v101, v101
	v_rcp_f32_e32 v102, v102
	v_rcp_f32_e32 v103, v103
	v_rcp_f32_e32 v104, v104
	v_rcp_f32_e32 v105, v105
	s_nop 0
	v_cvt_pk_bf16_f32 v172, v98, v99
	v_cvt_pk_bf16_f32 v173, v100, v101
	v_cvt_pk_bf16_f32 v174, v102, v103
	v_cvt_pk_bf16_f32 v175, v104, v105
	v_mul_f32_e32 v106, 0xbfb8aa3b, v106
; DI unsigned pack2(float a, float b) { f32v2 v = {a, b}; return __builtin_bit_cast(unsigned, __builtin_convertvector(v, bf16v2)); }
; DI float sigm_fast(float x) { return __builtin_amdgcn_rcpf(1.f + __expf(-x)); }
; DI void phase_merge(const Params& p, int l, char* smem, int tid) {
;     ...
; #pragma unroll
;         for (int b2 = 0; b2 < 2; b2++)
; #pragma unroll
;           for (int e = 0; e < 8; e++) sg[b2][e] = pack2(sigm_fast(m[0][b2][2 * e]), sigm_fast(m[0][b2][2 * e + 1]));
;       }
;       f32x16 t[1][2]; zero_acc<1>(t);
;       gemm_main<1>(p.G + (size_t)m0 * 1024 + i * 256, 1024, p.WtBr + ((size_t)l * 4 + i) * 1024 * 256 + (size_t)n0 * 256, 256, 256, t, s, tid);
	v_mul_f32_e32 v107, 0xbfb8aa3b, v107
	v_mul_f32_e32 v108, 0xbfb8aa3b, v108
	v_mul_f32_e32 v109, 0xbfb8aa3b, v109
	v_mul_f32_e32 v110, 0xbfb8aa3b, v110
	v_mul_f32_e32 v111, 0xbfb8aa3b, v111
	v_mul_f32_e32 v112, 0xbfb8aa3b, v112
	v_mul_f32_e32 v113, 0xbfb8aa3b, v113
	v_exp_f32_e32 v106, v106
	v_exp_f32_e32 v107, v107
	v_exp_f32_e32 v108, v108
	v_exp_f32_e32 v109, v109
	v_exp_f32_e32 v110, v110
	v_exp_f32_e32 v111, v111
	v_exp_f32_e32 v112, v112
	v_exp_f32_e32 v113, v113
	v_add_f32_e32 v106, 1.0, v106
	v_add_f32_e32 v107, 1.0, v107
	v_add_f32_e32 v108, 1.0, v108
	v_add_f32_e32 v109, 1.0, v109
	v_add_f32_e32 v110, 1.0, v110
	v_add_f32_e32 v111, 1.0, v111
	v_add_f32_e32 v112, 1.0, v112
	v_add_f32_e32 v113, 1.0, v113
	v_rcp_f32_e32 v106, v106
	v_rcp_f32_e32 v107, v107
	v_rcp_f32_e32 v108, v108
	v_rcp_f32_e32 v109, v109
	v_rcp_f32_e32 v110, v110
	v_rcp_f32_e32 v111, v111
	v_rcp_f32_e32 v112, v112
	v_rcp_f32_e32 v113, v113
	s_nop 0
	v_cvt_pk_bf16_f32 v176, v106, v107
	v_cvt_pk_bf16_f32 v177, v108, v109
	v_cvt_pk_bf16_f32 v178, v110, v111
	v_cvt_pk_bf16_f32 v179, v112, v113
	v_mul_f32_e32 v114, 0xbfb8aa3b, v114
	v_mul_f32_e32 v115, 0xbfb8aa3b, v115
	v_mul_f32_e32 v116, 0xbfb8aa3b, v116
	v_mul_f32_e32 v117, 0xbfb8aa3b, v117
	v_mul_f32_e32 v118, 0xbfb8aa3b, v118
	v_mul_f32_e32 v119, 0xbfb8aa3b, v119
	v_mul_f32_e32 v120, 0xbfb8aa3b, v120
	v_mul_f32_e32 v121, 0xbfb8aa3b, v121
	v_exp_f32_e32 v114, v114
	v_exp_f32_e32 v115, v115
	v_exp_f32_e32 v116, v116
	v_exp_f32_e32 v117, v117
	v_exp_f32_e32 v118, v118
	v_exp_f32_e32 v119, v119
	v_exp_f32_e32 v120, v120
	v_exp_f32_e32 v121, v121
	v_add_f32_e32 v114, 1.0, v114
	v_add_f32_e32 v115, 1.0, v115
	v_add_f32_e32 v116, 1.0, v116
	v_add_f32_e32 v117, 1.0, v117
	v_add_f32_e32 v118, 1.0, v118
	v_add_f32_e32 v119, 1.0, v119
	v_add_f32_e32 v120, 1.0, v120
	v_add_f32_e32 v121, 1.0, v121
	v_rcp_f32_e32 v114, v114
	v_rcp_f32_e32 v115, v115
	v_rcp_f32_e32 v116, v116
	v_rcp_f32_e32 v117, v117
	v_rcp_f32_e32 v118, v118
	v_rcp_f32_e32 v119, v119
	v_rcp_f32_e32 v120, v120
	v_rcp_f32_e32 v121, v121
	s_nop 0
	v_cvt_pk_bf16_f32 v180, v114, v115
	v_cvt_pk_bf16_f32 v181, v116, v117
	v_cvt_pk_bf16_f32 v182, v118, v119
	v_cvt_pk_bf16_f32 v183, v120, v121
	v_mul_f32_e32 v122, 0xbfb8aa3b, v122
	v_mul_f32_e32 v123, 0xbfb8aa3b, v123
	v_mul_f32_e32 v124, 0xbfb8aa3b, v124
	v_mul_f32_e32 v125, 0xbfb8aa3b, v125
	v_mul_f32_e32 v126, 0xbfb8aa3b, v126
	v_mul_f32_e32 v127, 0xbfb8aa3b, v127
	v_mul_f32_e32 v128, 0xbfb8aa3b, v128
	v_mul_f32_e32 v129, 0xbfb8aa3b, v129
	v_exp_f32_e32 v122, v122
	v_exp_f32_e32 v123, v123
	v_exp_f32_e32 v124, v124
	v_exp_f32_e32 v125, v125
	v_exp_f32_e32 v126, v126
	v_exp_f32_e32 v127, v127
	v_exp_f32_e32 v128, v128
	v_exp_f32_e32 v129, v129
	v_add_f32_e32 v122, 1.0, v122
	v_add_f32_e32 v123, 1.0, v123
	v_add_f32_e32 v124, 1.0, v124
	v_add_f32_e32 v125, 1.0, v125
	v_add_f32_e32 v126, 1.0, v126
	v_add_f32_e32 v127, 1.0, v127
	v_add_f32_e32 v128, 1.0, v128
	v_add_f32_e32 v129, 1.0, v129
	v_rcp_f32_e32 v122, v122
	v_rcp_f32_e32 v123, v123
	v_rcp_f32_e32 v124, v124
	v_rcp_f32_e32 v125, v125
	v_rcp_f32_e32 v126, v126
	v_rcp_f32_e32 v127, v127
	v_rcp_f32_e32 v128, v128
	v_rcp_f32_e32 v129, v129
	s_nop 0
	v_cvt_pk_bf16_f32 v184, v122, v123
	v_cvt_pk_bf16_f32 v185, v124, v125
	v_cvt_pk_bf16_f32 v186, v126, v127
	v_cvt_pk_bf16_f32 v187, v128, v129
	s_add_u32 s13, s13, 1
	v_mov_b32_e32 v66, 0
	v_mov_b32_e32 v67, 0
	v_mov_b32_e32 v68, 0
	v_mov_b32_e32 v69, 0
	v_mov_b32_e32 v70, 0
	v_mov_b32_e32 v71, 0
	v_mov_b32_e32 v72, 0
	v_mov_b32_e32 v73, 0
	v_mov_b32_e32 v74, 0
	v_mov_b32_e32 v75, 0
	v_mov_b32_e32 v76, 0
	v_mov_b32_e32 v77, 0
	v_mov_b32_e32 v78, 0
	v_mov_b32_e32 v79, 0
	v_mov_b32_e32 v80, 0
	v_mov_b32_e32 v81, 0
	v_mov_b32_e32 v82, 0
	v_mov_b32_e32 v83, 0
	v_mov_b32_e32 v84, 0
	v_mov_b32_e32 v85, 0
	v_mov_b32_e32 v86, 0
	v_mov_b32_e32 v87, 0
	v_mov_b32_e32 v88, 0
	v_mov_b32_e32 v89, 0
	v_mov_b32_e32 v90, 0
	v_mov_b32_e32 v91, 0
	v_mov_b32_e32 v92, 0
	v_mov_b32_e32 v93, 0
	v_mov_b32_e32 v94, 0
	v_mov_b32_e32 v95, 0
	v_mov_b32_e32 v96, 0
	v_mov_b32_e32 v97, 0
	v_mov_b32_e32 v98, 0
	v_mov_b32_e32 v99, 0
	v_mov_b32_e32 v100, 0
	v_mov_b32_e32 v101, 0
	v_mov_b32_e32 v102, 0
	v_mov_b32_e32 v103, 0
	v_mov_b32_e32 v104, 0
	v_mov_b32_e32 v105, 0
	v_mov_b32_e32 v106, 0
	v_mov_b32_e32 v107, 0
	v_mov_b32_e32 v108, 0
	v_mov_b32_e32 v109, 0
	v_mov_b32_e32 v110, 0
	v_mov_b32_e32 v111, 0
	v_mov_b32_e32 v112, 0
	v_mov_b32_e32 v113, 0
	v_mov_b32_e32 v114, 0
	v_mov_b32_e32 v115, 0
	v_mov_b32_e32 v116, 0
	v_mov_b32_e32 v117, 0
	v_mov_b32_e32 v118, 0
	v_mov_b32_e32 v119, 0
	v_mov_b32_e32 v120, 0
	v_mov_b32_e32 v121, 0
	v_mov_b32_e32 v122, 0
	v_mov_b32_e32 v123, 0
	v_mov_b32_e32 v124, 0
	v_mov_b32_e32 v125, 0
	v_mov_b32_e32 v126, 0
	v_mov_b32_e32 v127, 0
	v_mov_b32_e32 v128, 0
	v_mov_b32_e32 v129, 0
	s_waitcnt vmcnt(0) lgkmcnt(0)
	s_barrier
	ds_read_b128 v[224:227], v138 offset:0
	ds_read_b128 v[232:235], v142 offset:0
	ds_read_b128 v[228:231], v138 offset:4096
	ds_read_b128 v[236:239], v142 offset:4096
	s_add_u32 m0, s10, 0x8000
	s_nop 0
	global_load_lds_dwordx4 v200, s[4:5]
	s_add_u32 m0, s10, 0x8400
	s_nop 0
	global_load_lds_dwordx4 v201, s[4:5]
	s_add_u32 m0, s10, 0x8800
	s_nop 0
	global_load_lds_dwordx4 v202, s[4:5]
	s_add_u32 m0, s10, 0x8c00
	s_nop 0
	global_load_lds_dwordx4 v203, s[4:5]
	s_add_u32 s4, s4, 128
	s_addc_u32 s5, s5, 0
	s_mov_b32 s11, 1
	s_nop 0
